# attn tile loop: rotate slots with movs, single counter exit test, coalesced lgkmcnt waits, 2nd-piece LDS dst math in wait shadow
# speedup vs baseline: 1.0506x; 1.0109x over previous
; #define SBAR() __builtin_amdgcn_sched_barrier(0)
; #define WAIT_BAR(N) asm volatile("s_waitcnt vmcnt(" #N ") lgkmcnt(0)\n\ts_barrier":::"memory")
;   #define VRK(dst,vp_,ks_) do{ _Pragma("unroll") for(int d0_=0;d0_<4;++d0_){ dst[d0_]=*(const __attribute__((address_space(3))) bf16x8*)((vp_)+d0_*4096+(ks_)*1024); } }while(0)
; template<int THRL> __device__ __forceinline__ void attn_unit(int b,int h,int qb,const AttnArgs&A,char*shm,bool setup){
;     ...
;   for(int t=0;t<NT;++t){
;     WAIT_BAR(4);
;     const int kv0=t*KVBLK;
;     const bool act=(kv0<=qw0+QBLK-1);
;     const bool actn=(t+1<NT)&&(kv0+KVBLK<=qw0+QBLK-1);
;     const lds_cptr vp=vp0+vs_t;
;     const bool dk=(t+3<NT), dv=(t+2<NT);
;     const unsigned char*gk_=imgS+((size_t)(dk?t+3:NT-1)<<15); const unsigned char*gv_=imgS+((size_t)(dv?t+2:NT-1)<<15)+16384;
;     const unsigned kd_=(unsigned)__builtin_amdgcn_readfirstlane(dk?kdst+ks_t:ddst), vd_=(unsigned)__builtin_amdgcn_readfirstlane(dv?vdst+vs_nn:ddst);
;     if(act){
;       VRK(va,vp,0); VRK(vb,vp,1);
;       SBAR();
;       QKM(cini);
;     }
;     if(act){
;       const bool far=(qw0-(kv0+63)>=113);
;       if(!far){ const float*bt=biasT+mp*128; const int dq=qpos-kv0-4*hi;
;         #pragma unroll
;         for(int r=0;r<16;++r){ const int d=dq-((r&3)+8*(r>>2));
;           const int i0=d<0?0:(d>127?127:d);
;           const float b0=bt[i0];
;           const float n0=d>=0?0.f:-INFINITY;
;           p0[r]=(p0[r]+(b0-cfar))+n0; if((r&7)==7)asm volatile("":::"memory"); }
;         #pragma unroll
;         for(int r=0;r<16;++r){ const int d1=dq-32-((r&3)+8*(r>>2));
;           const int i1=d1<0?0:(d1>127?127:d1);
;           const float b1=bt[i1];
;           const float n1=d1>=0?0.f:-INFINITY;
;           p1[r]=(p1[r]+(b1-cfar))+n1; if((r&7)==7)asm volatile("":::"memory"); } }
;     ...
;     glds16s(gk_,voff,kd_); glds16s(gk_+8192,voff,kd_+8192); glds16s(gv_,voff,vd_); glds16s(gv_+8192,voff,vd_+8192);
;     ks_t=ks_n; ks_n=(ks_n==2*SLOT16)?0:ks_n+SLOT16; vs_t=(vs_t==2*SLOT16)?0:vs_t+SLOT16; vs_nn=(vs_nn==2*SLOT16)?0:vs_nn+SLOT16;
.LBB0_242:
	s_min_u32 s20, s81, 3
	s_or_b32 s80, s40, 31
	s_lshl_b32 s20, s20, 15
	s_add_u32 s94, s42, s20
	s_addc_u32 s95, s43, 0
	s_add_u32 s20, s8, 0x4000
	s_addc_u32 s21, s9, 0
	s_mov_b32 s40, m0
	s_mov_b32 m0, s82
	s_nop 0
	global_load_lds_dwordx4 v209, s[94:95]
	s_mov_b32 m0, s40
	s_add_u32 s94, s94, 0x2000
	s_addc_u32 s95, s95, 0
	s_addk_i32 s82, 0x2000
	s_mov_b32 s40, m0
	s_mov_b32 m0, s82
	s_nop 0
	global_load_lds_dwordx4 v209, s[94:95]
	s_mov_b32 m0, s40
	s_add_u32 s8, s8, 0x6000
	s_mov_b32 s40, m0
	s_mov_b32 m0, s73
	s_nop 0
	global_load_lds_dwordx4 v209, s[20:21]
	s_mov_b32 m0, s40
	s_addc_u32 s9, s9, 0
	s_addk_i32 s73, 0x2000
	s_mov_b32 s20, m0
	s_mov_b32 m0, s73
	s_nop 0
	global_load_lds_dwordx4 v209, s[8:9]
	s_mov_b32 m0, s20
	s_add_i32 s20, s22, s23
	s_mov_b32 s41, 3
	s_mov_b32 s9, 0
	s_add_i32 s8, s72, 2
	s_add_i32 s22, s20, 0xffffff81
	s_waitcnt vmcnt(8)
	v_sub_u32_e32 v14, v208, v212
	s_mov_b32 s23, 0x8000
	s_movk_i32 s73, 0x4000
	s_mov_b32 s40, 64
	s_movk_i32 s94, 0x4000
.LBB0_243:
	s_add_i32 s95, s41, 1
	s_add_i32 s20, s94, s46
	s_cmp_lt_i32 s41, s81
	s_cselect_b32 s82, s20, s98
	s_add_i32 s20, s9, s99
	s_waitcnt vmcnt(4) lgkmcnt(0)
	s_barrier
	s_cmp_lt_i32 s41, s72
	s_cselect_b32 s73, s20, s98
	s_cmp_lt_i32 s22, 0xffffffa2
	s_cbranch_scc1 .Ltr_inact
	v_add_u32_e32 v15, s94, v210
	ds_read_b128 v[162:165], v15 offset:49152
	ds_read_b128 v[146:149], v15 offset:50176
	ds_read_b128 v[158:161], v15 offset:53248
	ds_read_b128 v[10:13], v15 offset:54272
	ds_read_b128 v[154:157], v15 offset:57344
	ds_read_b128 v[6:9], v15 offset:58368
	ds_read_b128 v[150:153], v15 offset:61440
	ds_read_b128 v[2:5], v15 offset:62464
	v_mfma_f32_32x32x16_bf16 v[114:129], v[178:181], v[130:133], v[82:97]
	s_cmpk_gt_i32 s22, 0x70
	v_mfma_f32_32x32x16_bf16 v[98:113], v[182:185], v[130:133], v[82:97]
	v_mfma_f32_32x32x16_bf16 v[98:113], v[186:189], v[134:137], v[98:113]
	v_mfma_f32_32x32x16_bf16 v[114:129], v[166:169], v[134:137], v[114:129]
	v_mfma_f32_32x32x16_bf16 v[98:113], v[190:193], v[138:141], v[98:113]
	v_mfma_f32_32x32x16_bf16 v[114:129], v[174:177], v[138:141], v[114:129]
	v_mfma_f32_32x32x16_bf16 v[98:113], v[194:197], v[142:145], v[98:113]
	v_mfma_f32_32x32x16_bf16 v[114:129], v[170:173], v[142:145], v[114:129]
	s_cbranch_scc1 .LBB0_246
	v_add_u32_e32 v212, s22, v14
	s_sub_i32 s20, s29, 0x18800
	s_lshl_b32 s20, s20, 1
	s_add_i32 s20, s20, 0x1d000
	v_lshl_add_u32 v213, v212, 2, s20
	ds_read_b32 v166, v213 offset:504
	ds_read_b32 v167, v213 offset:500
	ds_read_b32 v168, v213 offset:496
	ds_read_b32 v169, v213 offset:492
	ds_read_b32 v170, v213 offset:472
	ds_read_b32 v171, v213 offset:468
	ds_read_b32 v172, v213 offset:464
	ds_read_b32 v173, v213 offset:460
	ds_read_b32 v174, v213 offset:440
	ds_read_b32 v175, v213 offset:436
	ds_read_b32 v176, v213 offset:432
	ds_read_b32 v177, v213 offset:428
	ds_read_b32 v178, v213 offset:408
	ds_read_b32 v179, v213 offset:404
	ds_read_b32 v180, v213 offset:400
	ds_read_b32 v181, v213 offset:396
	ds_read_b32 v182, v213 offset:376
	ds_read_b32 v183, v213 offset:372
	ds_read_b32 v184, v213 offset:368
	ds_read_b32 v185, v213 offset:364
	ds_read_b32 v186, v213 offset:344
	ds_read_b32 v187, v213 offset:340
	ds_read_b32 v188, v213 offset:336
	ds_read_b32 v189, v213 offset:332
	ds_read_b32 v190, v213 offset:312
	ds_read_b32 v191, v213 offset:308
	ds_read_b32 v192, v213 offset:304
	ds_read_b32 v193, v213 offset:300
	ds_read_b32 v194, v213 offset:280
	ds_read_b32 v195, v213 offset:276
	ds_read_b32 v196, v213 offset:272
	ds_read_b32 v197, v213 offset:268
	s_waitcnt lgkmcnt(14)
	v_pk_add_f32 v[114:115], v[114:115], v[166:167]
	v_pk_add_f32 v[116:117], v[116:117], v[168:169]
	v_pk_add_f32 v[118:119], v[118:119], v[170:171]
	v_pk_add_f32 v[120:121], v[120:121], v[172:173]
	v_pk_add_f32 v[122:123], v[122:123], v[174:175]
	v_pk_add_f32 v[124:125], v[124:125], v[176:177]
	v_pk_add_f32 v[126:127], v[126:127], v[178:179]
	v_pk_add_f32 v[128:129], v[128:129], v[180:181]
	s_waitcnt lgkmcnt(0)
	v_pk_add_f32 v[98:99], v[98:99], v[182:183]
	v_pk_add_f32 v[100:101], v[100:101], v[184:185]
	v_pk_add_f32 v[102:103], v[102:103], v[186:187]
	v_pk_add_f32 v[104:105], v[104:105], v[188:189]
	v_pk_add_f32 v[106:107], v[106:107], v[190:191]
	v_pk_add_f32 v[108:109], v[108:109], v[192:193]
	v_pk_add_f32 v[110:111], v[110:111], v[194:195]
	v_pk_add_f32 v[112:113], v[112:113], v[196:197]
; template<int THRL> __device__ __forceinline__ void attn_unit(int b,int h,int qb,const AttnArgs&A,char*shm,bool setup){
;     ...
;       const float rm=rowmax(p0,p1);
;       if(t==0||__any(rm>(float)THRL)){
;         const float dl=(t==0)?rm:__builtin_fmaxf(rm,0.f);
;         #pragma unroll
;         for(int r=0;r<16;++r){p0[r]-=dl;p1[r]-=dl;}
;         if(t>0){ const float f=__builtin_amdgcn_exp2f(-dl);
;           l*=f;
;           #pragma unroll
;           for(int d0=0;d0<4;++d0)
;             #pragma unroll
;             for(int r=0;r<16;++r)o[d0][r]*=f; }
;         mhat+=dl;
;         { const float ci=cfar-mhat;
;           #pragma unroll
;           for(int r=0;r<16;++r)cini[r]=ci;
;           asm volatile("":"+v"(cini)); }
.LBB0_246:
	s_min_i32 s20, s95, s81
	s_lshl_b32 s20, s20, 15
	s_add_u32 s20, s42, s20
	s_addc_u32 s21, s43, 0
	s_min_i32 s84, s41, s81
	s_lshl_b32 s84, s84, 15
	s_add_u32 s84, s34, s84
	s_addc_u32 s85, s35, 0
	s_add_i32 s83, s82, 0x2000
	s_add_i32 s95, s73, 0x2000
	v_max_f32_e32 v166, v98, v99
	v_max3_f32 v166, v166, v100, v101
	v_max3_f32 v167, v114, v115, v116
	v_max3_f32 v166, v166, v102, v103
	v_max3_f32 v167, v167, v117, v118
	v_max3_f32 v166, v166, v104, v105
	v_max3_f32 v167, v167, v119, v120
	v_max3_f32 v166, v166, v106, v107
	v_max3_f32 v167, v167, v121, v122
	v_max3_f32 v166, v166, v108, v109
	v_max3_f32 v167, v167, v123, v124
	v_max3_f32 v166, v166, v110, v111
	v_max3_f32 v167, v167, v125, v126
	v_max3_f32 v166, v166, v112, v113
	v_max3_f32 v167, v167, v127, v128
	v_max3_f32 v166, v167, v129, v166
	v_cmp_lt_f32_e32 vcc, 0x41000000, v166
	s_cbranch_vccz .LBB0_248
	v_mov_b32_e32 v167, v166
	s_nop 1
	v_permlane32_swap_b32_e32 v166, v167
	s_nop 1
	v_max_f32_e32 v166, v166, v167
	v_max_f32_e32 v82, v166, v166
	v_max_f32_e32 v82, 0, v82
	v_exp_f32_e64 v84, -v82
	v_add_f32_e32 v0, v0, v82
	v_pk_add_f32 v[114:115], v[114:115], v[82:83] op_sel_hi:[1,0] neg_lo:[0,1] neg_hi:[0,1]
	v_pk_add_f32 v[98:99], v[98:99], v[82:83] op_sel_hi:[1,0] neg_lo:[0,1] neg_hi:[0,1]
	v_pk_add_f32 v[116:117], v[116:117], v[82:83] op_sel_hi:[1,0] neg_lo:[0,1] neg_hi:[0,1]
	v_pk_add_f32 v[100:101], v[100:101], v[82:83] op_sel_hi:[1,0] neg_lo:[0,1] neg_hi:[0,1]
	v_pk_add_f32 v[118:119], v[118:119], v[82:83] op_sel_hi:[1,0] neg_lo:[0,1] neg_hi:[0,1]
	v_pk_add_f32 v[102:103], v[102:103], v[82:83] op_sel_hi:[1,0] neg_lo:[0,1] neg_hi:[0,1]
	v_pk_add_f32 v[120:121], v[120:121], v[82:83] op_sel_hi:[1,0] neg_lo:[0,1] neg_hi:[0,1]
	v_pk_add_f32 v[104:105], v[104:105], v[82:83] op_sel_hi:[1,0] neg_lo:[0,1] neg_hi:[0,1]
	v_pk_add_f32 v[122:123], v[122:123], v[82:83] op_sel_hi:[1,0] neg_lo:[0,1] neg_hi:[0,1]
	v_pk_add_f32 v[106:107], v[106:107], v[82:83] op_sel_hi:[1,0] neg_lo:[0,1] neg_hi:[0,1]
	v_pk_add_f32 v[124:125], v[124:125], v[82:83] op_sel_hi:[1,0] neg_lo:[0,1] neg_hi:[0,1]
	v_pk_add_f32 v[108:109], v[108:109], v[82:83] op_sel_hi:[1,0] neg_lo:[0,1] neg_hi:[0,1]
	v_pk_add_f32 v[126:127], v[126:127], v[82:83] op_sel_hi:[1,0] neg_lo:[0,1] neg_hi:[0,1]
	v_pk_add_f32 v[110:111], v[110:111], v[82:83] op_sel_hi:[1,0] neg_lo:[0,1] neg_hi:[0,1]
	v_pk_add_f32 v[128:129], v[128:129], v[82:83] op_sel_hi:[1,0] neg_lo:[0,1] neg_hi:[0,1]
	v_pk_add_f32 v[112:113], v[112:113], v[82:83] op_sel_hi:[1,0] neg_lo:[0,1] neg_hi:[0,1]
	v_sub_f32_e32 v82, v64, v0
	v_mul_f32_e32 v211, v211, v84
	v_pk_mul_f32 v[30:31], v[30:31], v[84:85] op_sel_hi:[1,0]
	v_pk_mul_f32 v[28:29], v[28:29], v[84:85] op_sel_hi:[1,0]
	v_pk_mul_f32 v[26:27], v[26:27], v[84:85] op_sel_hi:[1,0]
	v_pk_mul_f32 v[24:25], v[24:25], v[84:85] op_sel_hi:[1,0]
	v_pk_mul_f32 v[22:23], v[22:23], v[84:85] op_sel_hi:[1,0]
	v_pk_mul_f32 v[20:21], v[20:21], v[84:85] op_sel_hi:[1,0]
	v_pk_mul_f32 v[18:19], v[18:19], v[84:85] op_sel_hi:[1,0]
	v_pk_mul_f32 v[16:17], v[16:17], v[84:85] op_sel_hi:[1,0]
	v_pk_mul_f32 v[46:47], v[46:47], v[84:85] op_sel_hi:[1,0]
	v_pk_mul_f32 v[44:45], v[44:45], v[84:85] op_sel_hi:[1,0]
	v_pk_mul_f32 v[42:43], v[42:43], v[84:85] op_sel_hi:[1,0]
	v_pk_mul_f32 v[40:41], v[40:41], v[84:85] op_sel_hi:[1,0]
	v_pk_mul_f32 v[38:39], v[38:39], v[84:85] op_sel_hi:[1,0]
	v_pk_mul_f32 v[36:37], v[36:37], v[84:85] op_sel_hi:[1,0]
	v_pk_mul_f32 v[34:35], v[34:35], v[84:85] op_sel_hi:[1,0]
	v_pk_mul_f32 v[32:33], v[32:33], v[84:85] op_sel_hi:[1,0]
	v_pk_mul_f32 v[62:63], v[62:63], v[84:85] op_sel_hi:[1,0]
	v_pk_mul_f32 v[60:61], v[60:61], v[84:85] op_sel_hi:[1,0]
	v_pk_mul_f32 v[58:59], v[58:59], v[84:85] op_sel_hi:[1,0]
	v_pk_mul_f32 v[56:57], v[56:57], v[84:85] op_sel_hi:[1,0]
	v_pk_mul_f32 v[54:55], v[54:55], v[84:85] op_sel_hi:[1,0]
	v_pk_mul_f32 v[52:53], v[52:53], v[84:85] op_sel_hi:[1,0]
	v_pk_mul_f32 v[50:51], v[50:51], v[84:85] op_sel_hi:[1,0]
	v_pk_mul_f32 v[48:49], v[48:49], v[84:85] op_sel_hi:[1,0]
	v_pk_mul_f32 v[80:81], v[80:81], v[84:85] op_sel_hi:[1,0]
	v_pk_mul_f32 v[78:79], v[78:79], v[84:85] op_sel_hi:[1,0]
	v_pk_mul_f32 v[76:77], v[76:77], v[84:85] op_sel_hi:[1,0]
	v_pk_mul_f32 v[74:75], v[74:75], v[84:85] op_sel_hi:[1,0]
	v_pk_mul_f32 v[72:73], v[72:73], v[84:85] op_sel_hi:[1,0]
	v_pk_mul_f32 v[70:71], v[70:71], v[84:85] op_sel_hi:[1,0]
	v_pk_mul_f32 v[68:69], v[68:69], v[84:85] op_sel_hi:[1,0]
	v_pk_mul_f32 v[66:67], v[66:67], v[84:85] op_sel_hi:[1,0]
	v_mov_b32_e32 v83, v82
	v_mov_b32_e32 v84, v82
	v_mov_b32_e32 v85, v82
	v_mov_b32_e32 v86, v82
	v_mov_b32_e32 v87, v82
	v_mov_b32_e32 v88, v82
	v_mov_b32_e32 v89, v82
	v_mov_b32_e32 v90, v82
	v_mov_b32_e32 v91, v82
	v_mov_b32_e32 v92, v82
	v_mov_b32_e32 v93, v82
	v_mov_b32_e32 v94, v82
	v_mov_b32_e32 v95, v82
	v_mov_b32_e32 v96, v82
	v_mov_b32_e32 v97, v82
; #define SBAR() __builtin_amdgcn_sched_barrier(0)
;   #define KRD(kp_) do{ _Pragma("unroll") for(int d0_=0;d0_<4;++d0_){ kf[2*d0_]=LDK(kp_,d0_*2048); kf[2*d0_+1]=LDK(kp_,d0_*2048+512); } }while(0)
;   #define VRK(dst,vp_,ks_) do{ _Pragma("unroll") for(int d0_=0;d0_<4;++d0_){ dst[d0_]=*(const __attribute__((address_space(3))) bf16x8*)((vp_)+d0_*4096+(ks_)*1024); } }while(0)
;       #define QTR(P,B,W,I) do{ EX2(P,B); asm volatile("":"+v"(sacc)); { unsigned w_=cvtpk_s(P[B],P[B+1]); asm volatile("":"+v"(w_)); W[I]=w_; } }while(0)
;       #define PV1(d0_,ks_,src) o[d0_]=__builtin_amdgcn_mfma_f32_32x32x16_bf16(src[d0_],__builtin_bit_cast(bf16x8,pw[ks_]),o[d0_],0,0,0)
; template<int THRL> __device__ __forceinline__ void attn_unit(int b,int h,int qb,const AttnArgs&A,char*shm,bool setup){
;     ...
;       float sacc=0.f;
;       QTR(p0,0,pw[0],0); QTR(p0,2,pw[0],1); QTR(p0,4,pw[0],2); QTR(p0,6,pw[0],3);
;       SBAR();
;       PV1(0,0,va); QTR(p0,8,pw[1],0);  SBAR();
;       PV1(1,0,va); QTR(p0,10,pw[1],1); SBAR();
;       PV1(2,0,va); QTR(p0,12,pw[1],2); SBAR();
;       PV1(3,0,va); QTR(p0,14,pw[1],3); SBAR();
;       VRK(va,vp,2); SBAR();
;       PV1(0,1,vb); QTR(p1,0,pw[2],0);  SBAR();
;       PV1(1,1,vb); QTR(p1,2,pw[2],1);  SBAR();
;       PV1(2,1,vb); QTR(p1,4,pw[2],2);  SBAR();
;       PV1(3,1,vb); QTR(p1,6,pw[2],3);  SBAR();
;       VRK(vb,vp,3); SBAR();
;       PV1(0,2,va); QTR(p1,8,pw[3],0);  SBAR();
;       PV1(1,2,va); QTR(p1,10,pw[3],1); SBAR();
;       PV1(2,2,va); QTR(p1,12,pw[3],2); SBAR();
;       PV1(3,2,va); QTR(p1,14,pw[3],3); SBAR();
;       KRD(kp0+ks_n); SBAR();
;       PV1(0,3,vb); PV1(1,3,vb); PV1(2,3,vb); PV1(3,3,vb);
;       l+=sacc;
;       SBAR();
;     ...
;     }
;     glds16s(gk_,voff,kd_); glds16s(gk_+8192,voff,kd_+8192); glds16s(gv_,voff,vd_); glds16s(gv_+8192,voff,vd_+8192);
;     ks_t=ks_n; ks_n=(ks_n==2*SLOT16)?0:ks_n+SLOT16; vs_t=(vs_t==2*SLOT16)?0:vs_t+SLOT16; vs_nn=(vs_nn==2*SLOT16)?0:vs_nn+SLOT16;
.LBB0_248:
	v_exp_f32_e32 v114, v114
	v_exp_f32_e32 v115, v115
	v_exp_f32_e32 v116, v116
	v_exp_f32_e32 v117, v117
	v_exp_f32_e32 v118, v118
	v_add_f32_e32 v166, v115, v114
	v_exp_f32_e32 v119, v119
	v_cvt_pk_bf16_f32 v114, v114, v115
	v_add_f32_e32 v115, v116, v166
	v_add_f32_e32 v166, v117, v115
	v_exp_f32_e32 v120, v120
	v_cvt_pk_bf16_f32 v115, v116, v117
	v_add_f32_e32 v116, v118, v166
	v_exp_f32_e32 v121, v121
	v_add_f32_e32 v117, v119, v116
	v_cvt_pk_bf16_f32 v116, v118, v119
	v_add_f32_e32 v117, v120, v117
	v_add_f32_e32 v118, v121, v117
	v_cvt_pk_bf16_f32 v117, v120, v121
	s_waitcnt lgkmcnt(0)
	s_nop 0
	v_mfma_f32_32x32x16_bf16 v[66:81], v[162:165], v[114:117], v[66:81]
	v_exp_f32_e32 v119, v122
	v_exp_f32_e32 v120, v123
	v_add_f32_e32 v118, v119, v118
	v_add_f32_e32 v121, v120, v118
	v_cvt_pk_bf16_f32 v118, v119, v120
	v_mfma_f32_32x32x16_bf16 v[48:63], v[158:161], v[114:117], v[48:63]
	v_exp_f32_e32 v119, v124
	v_exp_f32_e32 v120, v125
	v_add_f32_e32 v121, v119, v121
	v_add_f32_e32 v121, v120, v121
	v_cvt_pk_bf16_f32 v119, v119, v120
	v_mfma_f32_32x32x16_bf16 v[32:47], v[154:157], v[114:117], v[32:47]
	v_exp_f32_e32 v120, v126
	v_exp_f32_e32 v122, v127
	v_add_f32_e32 v121, v120, v121
	v_add_f32_e32 v121, v122, v121
	v_cvt_pk_bf16_f32 v120, v120, v122
	v_mfma_f32_32x32x16_bf16 v[16:31], v[150:153], v[114:117], v[16:31]
	v_exp_f32_e32 v114, v128
	v_exp_f32_e32 v115, v129
	v_add_f32_e32 v116, v114, v121
	v_add_f32_e32 v154, v115, v116
	v_cvt_pk_bf16_f32 v121, v114, v115
	ds_read_b128 v[122:125], v15 offset:51200
	ds_read_b128 v[126:129], v15 offset:55296
	ds_read_b128 v[150:153], v15 offset:59392
	ds_read_b128 v[114:117], v15 offset:63488
	v_mfma_f32_32x32x16_bf16 v[66:81], v[146:149], v[118:121], v[66:81]
	v_exp_f32_e32 v98, v98
	v_exp_f32_e32 v99, v99
	v_add_f32_e32 v146, v98, v154
	v_add_f32_e32 v146, v99, v146
	v_cvt_pk_bf16_f32 v98, v98, v99
	v_mfma_f32_32x32x16_bf16 v[48:63], v[10:13], v[118:121], v[48:63]
	v_exp_f32_e32 v10, v100
	v_exp_f32_e32 v11, v101
	v_add_f32_e32 v12, v10, v146
	v_add_f32_e32 v12, v11, v12
	v_cvt_pk_bf16_f32 v99, v10, v11
	v_mfma_f32_32x32x16_bf16 v[32:47], v[6:9], v[118:121], v[32:47]
	v_exp_f32_e32 v6, v102
	v_exp_f32_e32 v7, v103
	v_add_f32_e32 v8, v6, v12
	v_add_f32_e32 v8, v7, v8
	v_cvt_pk_bf16_f32 v100, v6, v7
	v_mfma_f32_32x32x16_bf16 v[16:31], v[2:5], v[118:121], v[16:31]
	v_exp_f32_e32 v2, v104
	v_exp_f32_e32 v3, v105
	v_add_f32_e32 v4, v2, v8
	v_add_f32_e32 v118, v3, v4
	v_cvt_pk_bf16_f32 v101, v2, v3
	ds_read_b128 v[2:5], v15 offset:52224
	ds_read_b128 v[6:9], v15 offset:56320
	ds_read_b128 v[10:13], v15 offset:60416
	ds_read_b128 v[102:105], v15 offset:64512
	s_waitcnt lgkmcnt(4)
	v_mfma_f32_32x32x16_bf16 v[66:81], v[122:125], v[98:101], v[66:81]
	v_exp_f32_e32 v15, v106
	v_exp_f32_e32 v106, v107
	v_add_f32_e32 v107, v15, v118
	v_add_f32_e32 v107, v106, v107
	v_cvt_pk_bf16_f32 v106, v15, v106
	v_mfma_f32_32x32x16_bf16 v[48:63], v[126:129], v[98:101], v[48:63]
	v_exp_f32_e32 v15, v108
	v_exp_f32_e32 v108, v109
	v_add_f32_e32 v107, v15, v107
	v_add_f32_e32 v109, v108, v107
	v_cvt_pk_bf16_f32 v107, v15, v108
	v_mfma_f32_32x32x16_bf16 v[32:47], v[150:153], v[98:101], v[32:47]
	v_exp_f32_e32 v15, v110
	v_exp_f32_e32 v108, v111
	v_add_f32_e32 v109, v15, v109
	v_add_f32_e32 v109, v108, v109
	v_cvt_pk_bf16_f32 v108, v15, v108
	v_mfma_f32_32x32x16_bf16 v[16:31], v[114:117], v[98:101], v[16:31]
	v_exp_f32_e32 v15, v112
	v_exp_f32_e32 v98, v113
	v_add_f32_e32 v99, v15, v109
	v_add_f32_e32 v99, v98, v99
	v_cvt_pk_bf16_f32 v109, v15, v98
	v_add_u32_e32 v15, s23, v65
	ds_read_b128 v[178:181], v15
	ds_read_b128 v[182:185], v15 offset:512
	ds_read_b128 v[166:169], v15 offset:2048
	ds_read_b128 v[186:189], v15 offset:2560
	ds_read_b128 v[174:177], v15 offset:4096
	ds_read_b128 v[190:193], v15 offset:4608
	ds_read_b128 v[170:173], v15 offset:6144
	ds_read_b128 v[194:197], v15 offset:6656
	s_waitcnt lgkmcnt(8)
	v_mfma_f32_32x32x16_bf16 v[66:81], v[2:5], v[106:109], v[66:81]
	v_add_f32_e32 v211, v211, v99
	v_mfma_f32_32x32x16_bf16 v[48:63], v[6:9], v[106:109], v[48:63]
	v_mfma_f32_32x32x16_bf16 v[32:47], v[10:13], v[106:109], v[32:47]
	v_mfma_f32_32x32x16_bf16 v[16:31], v[102:105], v[106:109], v[16:31]
.LBB0_249:
	s_mov_b32 m0, s82
	s_add_i32 s41, s41, 1
	global_load_lds_dwordx4 v209, s[20:21]
	s_mov_b32 m0, s83
	s_add_u32 s20, s20, 0x2000
	s_addc_u32 s21, s21, 0
	global_load_lds_dwordx4 v209, s[20:21]
	s_mov_b32 m0, s73
	s_sub_i32 s22, s22, 64
	global_load_lds_dwordx4 v209, s[84:85]
	s_mov_b32 m0, s95
	s_add_u32 s84, s84, 0x2000
	s_addc_u32 s85, s85, 0
	global_load_lds_dwordx4 v209, s[84:85]
	s_mov_b32 s83, s94
	s_mov_b32 s94, s23
	s_mov_b32 s23, s9
	s_mov_b32 s9, s83
	s_cmp_lg_u32 s41, s8
	s_cbranch_scc1 .LBB0_243
	s_branch .LBB0_252
.Ltr_inact:
	s_min_i32 s20, s95, s81
	s_lshl_b32 s20, s20, 15
	s_add_u32 s20, s42, s20
	s_addc_u32 s21, s43, 0
	s_min_i32 s84, s41, s81
	s_lshl_b32 s84, s84, 15
	s_add_u32 s84, s34, s84
	s_addc_u32 s85, s35, 0
	s_add_i32 s83, s82, 0x2000
	s_add_i32 s95, s73, 0x2000
	s_branch .LBB0_249
